# v30
# baseline (speedup 1.0000x reference)
; __device__ __forceinline__ unsigned xb_ld(unsigned* p)              { return __hip_atomic_load(p, __ATOMIC_RELAXED, __HIP_MEMORY_SCOPE_AGENT); }
; __device__ __forceinline__ unsigned xb_add(unsigned* p, unsigned v) { return __hip_atomic_fetch_add(p, v, __ATOMIC_RELAXED, __HIP_MEMORY_SCOPE_AGENT); }
; #define XB_SPIN(cond, bar) do { unsigned _sp = 0; while (cond) { __builtin_amdgcn_s_sleep(1); \
;     if ((++_sp & 255u) == 0u) { if (xb_ld(&(bar)[XB_TMO])) break; if (_sp > XB_SPIN_CAP) { atomicAdd(&(bar)[XB_TMO], 1u); break; } } } } while (0)
; __device__ __forceinline__ void xcd_barrier(const XcdBarrier& b) {
;     ...
;         const unsigned old = xb_add(&bar[XB_XSUB(b.x)], 1u);
;         const unsigned gen = old / nloc;
;         if (old + 1u == (gen + 1u) * nloc) {
;             __builtin_amdgcn_fence(__ATOMIC_RELEASE, "agent");
;             asm volatile("s_waitcnt vmcnt(0)" ::: "memory");
;             const unsigned og = xb_add(&bar[XB_TOP], 1u);
;             const unsigned tg = og / nx;
;             if (og + 1u == (tg + 1u) * nx) xb_add(&bar[XB_TOPGEN], 1u);
;             else XB_SPIN(xb_ld(&bar[XB_TOPGEN]) == tg, bar);
.Llb_go_2:
	s_and_b32 s16, s2, 7
	s_lshl_b32 s16, s16, 8
	s_add_u32 s20, s14, 0x25d05000
	s_addc_u32 s21, s15, 0
	s_add_u32 s20, s20, s16
	s_addc_u32 s21, s21, 0
	v_mov_b32_e32 v2, 0
	v_mov_b32_e32 v3, 1
	global_atomic_add v4, v2, v3, s[20:21] sc0
	buffer_inv sc1
	s_waitcnt vmcnt(1)
	v_readfirstlane_b32 s17, v4
	s_lshr_b32 s22, s17, 5
	s_add_u32 s22, s22, 1
	s_lshl_b32 s22, s22, 5
	s_add_u32 s17, s17, 1
	s_and_b32 s17, s17, 31
	s_cmp_eq_u32 s17, 0
	s_cbranch_scc0 .Llb_wait_2
	s_branch .Llb_acq_2

; __device__ __forceinline__ unsigned xb_ld(unsigned* p)              { return __hip_atomic_load(p, __ATOMIC_RELAXED, __HIP_MEMORY_SCOPE_AGENT); }
; #define XB_SPIN(cond, bar) do { unsigned _sp = 0; while (cond) { __builtin_amdgcn_s_sleep(1); \
;     if ((++_sp & 255u) == 0u) { if (xb_ld(&(bar)[XB_TMO])) break; if (_sp > XB_SPIN_CAP) { atomicAdd(&(bar)[XB_TMO], 1u); break; } } } } while (0)
; __device__ __forceinline__ void xcd_barrier(const XcdBarrier& b) {
;     ...
;             XB_SPIN(xb_ld(&bar[XB_XGEN(b.x)]) == gen, bar);
;             __builtin_amdgcn_fence(__ATOMIC_ACQUIRE, "agent");
.Llb_spin_2:
	s_sleep 1
	global_load_dword v4, v2, s[20:21] sc1
	s_waitcnt vmcnt(0)
	v_readfirstlane_b32 s24, v4
	s_cmp_ge_u32 s24, s22
	s_cbranch_scc1 .Llb_acq_2
	s_add_u32 s23, s23, 1
	s_cmp_lt_u32 s23, 0x100000
	s_cbranch_scc1 .Llb_spin_2

; __device__ __forceinline__ unsigned xb_ld(unsigned* p)              { return __hip_atomic_load(p, __ATOMIC_RELAXED, __HIP_MEMORY_SCOPE_AGENT); }
; __device__ __forceinline__ unsigned xb_add(unsigned* p, unsigned v) { return __hip_atomic_fetch_add(p, v, __ATOMIC_RELAXED, __HIP_MEMORY_SCOPE_AGENT); }
; #define XB_SPIN(cond, bar) do { unsigned _sp = 0; while (cond) { __builtin_amdgcn_s_sleep(1); \
;     if ((++_sp & 255u) == 0u) { if (xb_ld(&(bar)[XB_TMO])) break; if (_sp > XB_SPIN_CAP) { atomicAdd(&(bar)[XB_TMO], 1u); break; } } } } while (0)
; __device__ __forceinline__ void xcd_barrier(const XcdBarrier& b) {
;     ...
;         const unsigned old = xb_add(&bar[XB_XSUB(b.x)], 1u);
;         const unsigned gen = old / nloc;
;         if (old + 1u == (gen + 1u) * nloc) {
;             __builtin_amdgcn_fence(__ATOMIC_RELEASE, "agent");
;             asm volatile("s_waitcnt vmcnt(0)" ::: "memory");
;             const unsigned og = xb_add(&bar[XB_TOP], 1u);
;             const unsigned tg = og / nx;
;             if (og + 1u == (tg + 1u) * nx) xb_add(&bar[XB_TOPGEN], 1u);
;             else XB_SPIN(xb_ld(&bar[XB_TOPGEN]) == tg, bar);
.Llb_go_5:
	s_add_u32 s22, s14, 0x25d06000
	s_addc_u32 s23, s15, 0
	v_mov_b32_e32 v2, 0
	v_mov_b32_e32 v3, 1
	global_atomic_add v2, v3, s[22:23]
	s_and_b32 s16, s2, 7
	s_lshl_b32 s16, s16, 8
	s_add_u32 s20, s14, 0x25d05000
	s_addc_u32 s21, s15, 0
	s_add_u32 s20, s20, s16
	s_addc_u32 s21, s21, 0
	v_mov_b32_e32 v2, 0
	v_mov_b32_e32 v3, 1
	global_atomic_add v4, v2, v3, s[20:21] sc0
	buffer_inv sc1
	s_waitcnt vmcnt(1)
	v_readfirstlane_b32 s17, v4
	s_lshr_b32 s22, s17, 5
	s_add_u32 s22, s22, 1
	s_lshl_b32 s22, s22, 5
	s_add_u32 s17, s17, 1
	s_and_b32 s17, s17, 31
	s_cmp_eq_u32 s17, 0
	s_cbranch_scc0 .Llb_wait_5
	s_branch .Llb_acq_5
